# lever 1 on the down-GEMM epilogue: one wait for a row batch's four residual loads in front of its first store, the three later counted waits (which also drained the batch's own stores/atomics) removed
# speedup vs baseline: 1.0110x; 1.0029x over previous
;     __device__ __forceinline__ void operator()(const f32x4 (&acc)[2][2][4][2], const Unit& u, int wr, int wc, int fr, int fq) const {
;     ...
;                     for (int bj = 0; bj < 2; ++bj) rw[m - m0][bj] = *(const u32x4*)((const bf16_t*)r0 + (size_t)(row0 + ai * HALF + m * 16) * D + col0 + bj * HALF);
; #pragma unroll
;                 for (int m = m0; m < m0 + 2; ++m)
; #pragma unroll
;                     for (int bj = 0; bj < 2; ++bj) { const u32x4 x = rw[m - m0][bj];
;                         rv[m][bj][0] = (f32x4){__builtin_bit_cast(float, x.x << 16), __builtin_bit_cast(float, x.x & 0xffff0000u), __builtin_bit_cast(float, x.y << 16), __builtin_bit_cast(float, x.y & 0xffff0000u)};
;                         rv[m][bj][1] = (f32x4){__builtin_bit_cast(float, x.z << 16), __builtin_bit_cast(float, x.z & 0xffff0000u), __builtin_bit_cast(float, x.w << 16), __builtin_bit_cast(float, x.w & 0xffff0000u)}; }
;             } else {
; #pragma unroll
;                 for (int m = m0; m < m0 + 2; ++m) { const float* rp = (const float*)r0 + (size_t)(row0 + ai * HALF + m * 16) * D + col0;
; #pragma unroll
;                     for (int bj = 0; bj < 2; ++bj) { rv[m][bj][0] = *(const f32x4*)(rp + bj * HALF); rv[m][bj][1] = *(const f32x4*)(rp + bj * HALF + 4); } }
;             }
; #pragma unroll
;             for (int m = m0; m < m0 + 2; ++m) { const int row = row0 + ai * HALF + m * 16;
;                 float ss = 0.f;
; #pragma unroll
;                 for (int bj = 0; bj < 2; ++bj) { const f32x4 v0 = acc[ai][bj][m][0] + rv[m][bj][0], v1 = acc[ai][bj][m][1] + rv[m][bj][1];
;                     if (out) { float* op = out + (size_t)row * D + col0 + bj * HALF; *(f32x4*)op = v0; *(f32x4*)(op + 4) = v1; }
.LBB0_1706:
	v_or_b32_e32 v122, 32, v154
	v_ashrrev_i32_e32 v123, 31, v122
	v_or_b32_e32 v114, 48, v154
	v_lshlrev_b64 v[116:117], 12, v[122:123]
	v_ashrrev_i32_e32 v115, 31, v114
	v_lshl_add_u64 v[100:101], v[158:159], 0, v[116:117]
	v_lshlrev_b64 v[112:113], 12, v[114:115]
	global_load_dwordx4 v[118:121], v[100:101], off
	v_lshl_add_u64 v[102:103], v[158:159], 0, v[112:113]
	global_load_dwordx4 v[108:111], v[100:101], off offset:256
	s_waitcnt lgkmcnt(0)
	global_load_dwordx4 v[104:107], v[102:103], off
	s_nop 0
	global_load_dwordx4 v[100:103], v[102:103], off offset:256
	v_lshlrev_b64 v[122:123], 13, v[122:123]
	v_lshl_add_u64 v[122:123], s[12:13], 0, v[122:123]
	s_and_b64 vcc, exec, s[46:47]
	s_waitcnt vmcnt(0)
	v_lshlrev_b32_e32 v124, 16, v118
	v_and_b32_e32 v125, 0xffff0000, v118
	v_lshlrev_b32_e32 v118, 16, v119
	v_and_b32_e32 v119, 0xffff0000, v119
	v_lshlrev_b32_e32 v126, 16, v120
	v_and_b32_e32 v127, 0xffff0000, v120
	v_lshlrev_b32_e32 v120, 16, v121
	v_and_b32_e32 v121, 0xffff0000, v121
	v_pk_add_f32 v[98:99], v[98:99], v[118:119]
	v_pk_add_f32 v[96:97], v[96:97], v[124:125]
	v_pk_add_f32 v[94:95], v[94:95], v[120:121]
	v_pk_add_f32 v[92:93], v[92:93], v[126:127]
	v_lshl_add_u64 v[118:119], v[156:157], 2, v[122:123]
	s_cbranch_vccnz .LBB0_1708
	global_store_dwordx4 v[118:119], v[96:99], off
	global_store_dwordx4 v[118:119], v[92:95], off offset:16

;     __device__ __forceinline__ void operator()(const f32x4 (&acc)[2][2][4][2], const Unit& u, int wr, int wc, int fr, int fq) const {
;     ...
;             for (int m = m0; m < m0 + 2; ++m) { const int row = row0 + ai * HALF + m * 16;
;                 float ss = 0.f;
; #pragma unroll
;                 for (int bj = 0; bj < 2; ++bj) { const f32x4 v0 = acc[ai][bj][m][0] + rv[m][bj][0], v1 = acc[ai][bj][m][1] + rv[m][bj][1];
;                     if (out) { float* op = out + (size_t)row * D + col0 + bj * HALF; *(f32x4*)op = v0; *(f32x4*)(op + 4) = v1; }
.LBB0_1711:
	v_lshlrev_b32_e32 v92, 16, v108
	v_and_b32_e32 v93, 0xffff0000, v108
	v_lshlrev_b32_e32 v94, 16, v109
	v_and_b32_e32 v95, 0xffff0000, v109
	v_lshlrev_b32_e32 v96, 16, v110
	v_and_b32_e32 v97, 0xffff0000, v110
	v_lshlrev_b32_e32 v98, 16, v111
	v_and_b32_e32 v99, 0xffff0000, v111
	v_pk_add_f32 v[90:91], v[90:91], v[94:95]
	v_pk_add_f32 v[88:89], v[88:89], v[92:93]
	v_pk_add_f32 v[86:87], v[86:87], v[98:99]
	s_and_b64 vcc, exec, s[46:47]
	v_pk_add_f32 v[84:85], v[84:85], v[96:97]
	s_cbranch_vccnz .LBB0_1713
	global_store_dwordx4 v[118:119], v[88:91], off offset:512
	global_store_dwordx4 v[118:119], v[84:87], off offset:528

;     __device__ __forceinline__ void operator()(const f32x4 (&acc)[2][2][4][2], const Unit& u, int wr, int wc, int fr, int fq) const {
;     ...
;             for (int m = m0; m < m0 + 2; ++m) { const int row = row0 + ai * HALF + m * 16;
;                 float ss = 0.f;
; #pragma unroll
;                 for (int bj = 0; bj < 2; ++bj) { const f32x4 v0 = acc[ai][bj][m][0] + rv[m][bj][0], v1 = acc[ai][bj][m][1] + rv[m][bj][1];
;                     if (out) { float* op = out + (size_t)row * D + col0 + bj * HALF; *(f32x4*)op = v0; *(f32x4*)(op + 4) = v1; }
.LBB0_1717:
	v_lshlrev_b32_e32 v84, 16, v104
	v_and_b32_e32 v85, 0xffff0000, v104
	v_lshlrev_b64 v[92:93], 13, v[114:115]
	v_lshlrev_b32_e32 v86, 16, v105
	v_and_b32_e32 v87, 0xffff0000, v105
	v_lshlrev_b32_e32 v88, 16, v106
	s_waitcnt lgkmcnt(0)
	v_and_b32_e32 v89, 0xffff0000, v106
	v_lshlrev_b32_e32 v90, 16, v107
	v_and_b32_e32 v91, 0xffff0000, v107
	v_pk_add_f32 v[80:81], v[80:81], v[84:85]
	v_lshl_add_u64 v[84:85], s[12:13], 0, v[92:93]
	v_pk_add_f32 v[82:83], v[82:83], v[86:87]
	v_pk_add_f32 v[78:79], v[78:79], v[90:91]
	v_pk_add_f32 v[76:77], v[76:77], v[88:89]
	s_and_b64 vcc, exec, s[46:47]
	v_lshl_add_u64 v[86:87], v[156:157], 2, v[84:85]
	s_cbranch_vccnz .LBB0_1719
	global_store_dwordx4 v[86:87], v[80:83], off
	global_store_dwordx4 v[86:87], v[76:79], off offset:16

;     __device__ __forceinline__ void operator()(const f32x4 (&acc)[2][2][4][2], const Unit& u, int wr, int wc, int fr, int fq) const {
;     ...
;             for (int m = m0; m < m0 + 2; ++m) { const int row = row0 + ai * HALF + m * 16;
;                 float ss = 0.f;
; #pragma unroll
;                 for (int bj = 0; bj < 2; ++bj) { const f32x4 v0 = acc[ai][bj][m][0] + rv[m][bj][0], v1 = acc[ai][bj][m][1] + rv[m][bj][1];
;                     if (out) { float* op = out + (size_t)row * D + col0 + bj * HALF; *(f32x4*)op = v0; *(f32x4*)(op + 4) = v1; }
.LBB0_1722:
	v_lshlrev_b32_e32 v76, 16, v100
	v_and_b32_e32 v77, 0xffff0000, v100
	v_lshlrev_b32_e32 v78, 16, v101
	v_and_b32_e32 v79, 0xffff0000, v101
	v_lshlrev_b32_e32 v80, 16, v102
	v_and_b32_e32 v81, 0xffff0000, v102
	v_lshlrev_b32_e32 v82, 16, v103
	v_and_b32_e32 v83, 0xffff0000, v103
	v_pk_add_f32 v[74:75], v[74:75], v[78:79]
	v_pk_add_f32 v[72:73], v[72:73], v[76:77]
	v_pk_add_f32 v[70:71], v[70:71], v[82:83]
	s_and_b64 vcc, exec, s[46:47]
	v_pk_add_f32 v[68:69], v[68:69], v[80:81]
	s_cbranch_vccnz .LBB0_1724
	global_store_dwordx4 v[86:87], v[72:75], off offset:512
	global_store_dwordx4 v[86:87], v[68:71], off offset:528

;     __device__ __forceinline__ void operator()(const f32x4 (&acc)[2][2][4][2], const Unit& u, int wr, int wc, int fr, int fq) const {
;     ...
;                     for (int bj = 0; bj < 2; ++bj) rw[m - m0][bj] = *(const u32x4*)((const bf16_t*)r0 + (size_t)(row0 + ai * HALF + m * 16) * D + col0 + bj * HALF);
; #pragma unroll
;                 for (int m = m0; m < m0 + 2; ++m)
; #pragma unroll
;                     for (int bj = 0; bj < 2; ++bj) { const u32x4 x = rw[m - m0][bj];
;                         rv[m][bj][0] = (f32x4){__builtin_bit_cast(float, x.x << 16), __builtin_bit_cast(float, x.x & 0xffff0000u), __builtin_bit_cast(float, x.y << 16), __builtin_bit_cast(float, x.y & 0xffff0000u)};
;                         rv[m][bj][1] = (f32x4){__builtin_bit_cast(float, x.z << 16), __builtin_bit_cast(float, x.z & 0xffff0000u), __builtin_bit_cast(float, x.w << 16), __builtin_bit_cast(float, x.w & 0xffff0000u)}; }
;             } else {
; #pragma unroll
;                 for (int m = m0; m < m0 + 2; ++m) { const float* rp = (const float*)r0 + (size_t)(row0 + ai * HALF + m * 16) * D + col0;
; #pragma unroll
;                     for (int bj = 0; bj < 2; ++bj) { rv[m][bj][0] = *(const f32x4*)(rp + bj * HALF); rv[m][bj][1] = *(const f32x4*)(rp + bj * HALF + 4); } }
;             }
; #pragma unroll
;             for (int m = m0; m < m0 + 2; ++m) { const int row = row0 + ai * HALF + m * 16;
;                 float ss = 0.f;
; #pragma unroll
;                 for (int bj = 0; bj < 2; ++bj) { const f32x4 v0 = acc[ai][bj][m][0] + rv[m][bj][0], v1 = acc[ai][bj][m][1] + rv[m][bj][1];
;                     if (out) { float* op = out + (size_t)row * D + col0 + bj * HALF; *(f32x4*)op = v0; *(f32x4*)(op + 4) = v1; }
.LBB0_1728:
	v_add_u32_e32 v90, 0x80, v154
	v_ashrrev_i32_e32 v91, 31, v90
	v_add_u32_e32 v82, 0x90, v154
	v_lshlrev_b64 v[84:85], 12, v[90:91]
	v_ashrrev_i32_e32 v83, 31, v82
	v_lshl_add_u64 v[68:69], v[158:159], 0, v[84:85]
	v_lshlrev_b64 v[80:81], 12, v[82:83]
	global_load_dwordx4 v[86:89], v[68:69], off
	v_lshl_add_u64 v[70:71], v[158:159], 0, v[80:81]
	global_load_dwordx4 v[76:79], v[68:69], off offset:256
	s_waitcnt lgkmcnt(0)
	global_load_dwordx4 v[72:75], v[70:71], off
	s_nop 0
	global_load_dwordx4 v[68:71], v[70:71], off offset:256
	v_lshlrev_b64 v[90:91], 13, v[90:91]
	v_lshl_add_u64 v[90:91], s[12:13], 0, v[90:91]
	s_and_b64 vcc, exec, s[46:47]
	s_waitcnt vmcnt(0)
	v_lshlrev_b32_e32 v92, 16, v86
	v_and_b32_e32 v93, 0xffff0000, v86
	v_lshlrev_b32_e32 v86, 16, v87
	v_and_b32_e32 v87, 0xffff0000, v87
	v_lshlrev_b32_e32 v94, 16, v88
	v_and_b32_e32 v95, 0xffff0000, v88
	v_lshlrev_b32_e32 v88, 16, v89
	v_and_b32_e32 v89, 0xffff0000, v89
	v_pk_add_f32 v[66:67], v[66:67], v[86:87]
	v_pk_add_f32 v[64:65], v[64:65], v[92:93]
	v_pk_add_f32 v[62:63], v[62:63], v[88:89]
	v_pk_add_f32 v[60:61], v[60:61], v[94:95]
	v_lshl_add_u64 v[86:87], v[156:157], 2, v[90:91]
	s_cbranch_vccnz .LBB0_1730
	global_store_dwordx4 v[86:87], v[64:67], off
	global_store_dwordx4 v[86:87], v[60:63], off offset:16

;     __device__ __forceinline__ void operator()(const f32x4 (&acc)[2][2][4][2], const Unit& u, int wr, int wc, int fr, int fq) const {
;     ...
;             for (int m = m0; m < m0 + 2; ++m) { const int row = row0 + ai * HALF + m * 16;
;                 float ss = 0.f;
; #pragma unroll
;                 for (int bj = 0; bj < 2; ++bj) { const f32x4 v0 = acc[ai][bj][m][0] + rv[m][bj][0], v1 = acc[ai][bj][m][1] + rv[m][bj][1];
;                     if (out) { float* op = out + (size_t)row * D + col0 + bj * HALF; *(f32x4*)op = v0; *(f32x4*)(op + 4) = v1; }
.LBB0_1733:
	v_lshlrev_b32_e32 v60, 16, v76
	v_and_b32_e32 v61, 0xffff0000, v76
	v_lshlrev_b32_e32 v62, 16, v77
	v_and_b32_e32 v63, 0xffff0000, v77
	v_lshlrev_b32_e32 v64, 16, v78
	v_and_b32_e32 v65, 0xffff0000, v78
	v_lshlrev_b32_e32 v66, 16, v79
	v_and_b32_e32 v67, 0xffff0000, v79
	v_pk_add_f32 v[58:59], v[58:59], v[62:63]
	v_pk_add_f32 v[56:57], v[56:57], v[60:61]
	v_pk_add_f32 v[54:55], v[54:55], v[66:67]
	s_and_b64 vcc, exec, s[46:47]
	v_pk_add_f32 v[52:53], v[52:53], v[64:65]
	s_cbranch_vccnz .LBB0_1735
	global_store_dwordx4 v[86:87], v[56:59], off offset:512
	global_store_dwordx4 v[86:87], v[52:55], off offset:528

;     __device__ __forceinline__ void operator()(const f32x4 (&acc)[2][2][4][2], const Unit& u, int wr, int wc, int fr, int fq) const {
;     ...
;             for (int m = m0; m < m0 + 2; ++m) { const int row = row0 + ai * HALF + m * 16;
;                 float ss = 0.f;
; #pragma unroll
;                 for (int bj = 0; bj < 2; ++bj) { const f32x4 v0 = acc[ai][bj][m][0] + rv[m][bj][0], v1 = acc[ai][bj][m][1] + rv[m][bj][1];
;                     if (out) { float* op = out + (size_t)row * D + col0 + bj * HALF; *(f32x4*)op = v0; *(f32x4*)(op + 4) = v1; }
.LBB0_1739:
	v_lshlrev_b32_e32 v52, 16, v72
	v_and_b32_e32 v53, 0xffff0000, v72
	v_lshlrev_b64 v[60:61], 13, v[82:83]
	v_lshlrev_b32_e32 v54, 16, v73
	v_and_b32_e32 v55, 0xffff0000, v73
	v_lshlrev_b32_e32 v56, 16, v74
	s_waitcnt lgkmcnt(0)
	v_and_b32_e32 v57, 0xffff0000, v74
	v_lshlrev_b32_e32 v58, 16, v75
	v_and_b32_e32 v59, 0xffff0000, v75
	v_pk_add_f32 v[48:49], v[48:49], v[52:53]
	v_lshl_add_u64 v[52:53], s[12:13], 0, v[60:61]
	v_pk_add_f32 v[50:51], v[50:51], v[54:55]
	v_pk_add_f32 v[46:47], v[46:47], v[58:59]
	v_pk_add_f32 v[44:45], v[44:45], v[56:57]
	s_and_b64 vcc, exec, s[46:47]
	v_lshl_add_u64 v[54:55], v[156:157], 2, v[52:53]
	s_cbranch_vccnz .LBB0_1741
	global_store_dwordx4 v[54:55], v[48:51], off
	global_store_dwordx4 v[54:55], v[44:47], off offset:16

;     __device__ __forceinline__ void operator()(const f32x4 (&acc)[2][2][4][2], const Unit& u, int wr, int wc, int fr, int fq) const {
;     ...
;             for (int m = m0; m < m0 + 2; ++m) { const int row = row0 + ai * HALF + m * 16;
;                 float ss = 0.f;
; #pragma unroll
;                 for (int bj = 0; bj < 2; ++bj) { const f32x4 v0 = acc[ai][bj][m][0] + rv[m][bj][0], v1 = acc[ai][bj][m][1] + rv[m][bj][1];
;                     if (out) { float* op = out + (size_t)row * D + col0 + bj * HALF; *(f32x4*)op = v0; *(f32x4*)(op + 4) = v1; }
.LBB0_1744:
	v_lshlrev_b32_e32 v44, 16, v68
	v_and_b32_e32 v45, 0xffff0000, v68
	v_lshlrev_b32_e32 v46, 16, v69
	v_and_b32_e32 v47, 0xffff0000, v69
	v_lshlrev_b32_e32 v48, 16, v70
	v_and_b32_e32 v49, 0xffff0000, v70
	v_lshlrev_b32_e32 v50, 16, v71
	v_and_b32_e32 v51, 0xffff0000, v71
	v_pk_add_f32 v[42:43], v[42:43], v[46:47]
	v_pk_add_f32 v[40:41], v[40:41], v[44:45]
	v_pk_add_f32 v[38:39], v[38:39], v[50:51]
	s_and_b64 vcc, exec, s[46:47]
	v_pk_add_f32 v[36:37], v[36:37], v[48:49]
	s_cbranch_vccnz .LBB0_1746
	global_store_dwordx4 v[54:55], v[40:43], off offset:512
	global_store_dwordx4 v[54:55], v[36:39], off offset:528

;     __device__ __forceinline__ void operator()(const f32x4 (&acc)[2][2][4][2], const Unit& u, int wr, int wc, int fr, int fq) const {
;     ...
;                     for (int bj = 0; bj < 2; ++bj) rw[m - m0][bj] = *(const u32x4*)((const bf16_t*)r0 + (size_t)(row0 + ai * HALF + m * 16) * D + col0 + bj * HALF);
; #pragma unroll
;                 for (int m = m0; m < m0 + 2; ++m)
; #pragma unroll
;                     for (int bj = 0; bj < 2; ++bj) { const u32x4 x = rw[m - m0][bj];
;                         rv[m][bj][0] = (f32x4){__builtin_bit_cast(float, x.x << 16), __builtin_bit_cast(float, x.x & 0xffff0000u), __builtin_bit_cast(float, x.y << 16), __builtin_bit_cast(float, x.y & 0xffff0000u)};
;                         rv[m][bj][1] = (f32x4){__builtin_bit_cast(float, x.z << 16), __builtin_bit_cast(float, x.z & 0xffff0000u), __builtin_bit_cast(float, x.w << 16), __builtin_bit_cast(float, x.w & 0xffff0000u)}; }
;             } else {
; #pragma unroll
;                 for (int m = m0; m < m0 + 2; ++m) { const float* rp = (const float*)r0 + (size_t)(row0 + ai * HALF + m * 16) * D + col0;
; #pragma unroll
;                     for (int bj = 0; bj < 2; ++bj) { rv[m][bj][0] = *(const f32x4*)(rp + bj * HALF); rv[m][bj][1] = *(const f32x4*)(rp + bj * HALF + 4); } }
;             }
; #pragma unroll
;             for (int m = m0; m < m0 + 2; ++m) { const int row = row0 + ai * HALF + m * 16;
;                 float ss = 0.f;
; #pragma unroll
;                 for (int bj = 0; bj < 2; ++bj) { const f32x4 v0 = acc[ai][bj][m][0] + rv[m][bj][0], v1 = acc[ai][bj][m][1] + rv[m][bj][1];
;                     if (out) { float* op = out + (size_t)row * D + col0 + bj * HALF; *(f32x4*)op = v0; *(f32x4*)(op + 4) = v1; }
.LBB0_1750:
	v_add_u32_e32 v58, 0xa0, v154
	v_ashrrev_i32_e32 v59, 31, v58
	v_add_u32_e32 v50, 0xb0, v154
	v_lshlrev_b64 v[52:53], 12, v[58:59]
	v_ashrrev_i32_e32 v51, 31, v50
	v_lshl_add_u64 v[36:37], v[158:159], 0, v[52:53]
	v_lshlrev_b64 v[48:49], 12, v[50:51]
	global_load_dwordx4 v[54:57], v[36:37], off
	v_lshl_add_u64 v[38:39], v[158:159], 0, v[48:49]
	global_load_dwordx4 v[44:47], v[36:37], off offset:256
	s_waitcnt lgkmcnt(0)
	global_load_dwordx4 v[40:43], v[38:39], off
	s_nop 0
	global_load_dwordx4 v[36:39], v[38:39], off offset:256
	v_lshlrev_b64 v[58:59], 13, v[58:59]
	v_lshl_add_u64 v[58:59], s[12:13], 0, v[58:59]
	s_and_b64 vcc, exec, s[46:47]
	s_waitcnt vmcnt(0)
	v_lshlrev_b32_e32 v60, 16, v54
	v_and_b32_e32 v61, 0xffff0000, v54
	v_lshlrev_b32_e32 v54, 16, v55
	v_and_b32_e32 v55, 0xffff0000, v55
	v_lshlrev_b32_e32 v62, 16, v56
	v_and_b32_e32 v63, 0xffff0000, v56
	v_lshlrev_b32_e32 v56, 16, v57
	v_and_b32_e32 v57, 0xffff0000, v57
	v_pk_add_f32 v[32:33], v[32:33], v[54:55]
	v_pk_add_f32 v[30:31], v[30:31], v[60:61]
	v_pk_add_f32 v[28:29], v[28:29], v[56:57]
	v_pk_add_f32 v[26:27], v[26:27], v[62:63]
	v_lshl_add_u64 v[54:55], v[156:157], 2, v[58:59]
	s_cbranch_vccnz .LBB0_1752
	global_store_dwordx4 v[54:55], v[30:33], off
	global_store_dwordx4 v[54:55], v[26:29], off offset:16

;     __device__ __forceinline__ void operator()(const f32x4 (&acc)[2][2][4][2], const Unit& u, int wr, int wc, int fr, int fq) const {
;     ...
;             for (int m = m0; m < m0 + 2; ++m) { const int row = row0 + ai * HALF + m * 16;
;                 float ss = 0.f;
; #pragma unroll
;                 for (int bj = 0; bj < 2; ++bj) { const f32x4 v0 = acc[ai][bj][m][0] + rv[m][bj][0], v1 = acc[ai][bj][m][1] + rv[m][bj][1];
;                     if (out) { float* op = out + (size_t)row * D + col0 + bj * HALF; *(f32x4*)op = v0; *(f32x4*)(op + 4) = v1; }
.LBB0_1755:
	v_lshlrev_b32_e32 v26, 16, v44
	v_and_b32_e32 v27, 0xffff0000, v44
	v_lshlrev_b32_e32 v28, 16, v45
	v_and_b32_e32 v29, 0xffff0000, v45
	v_lshlrev_b32_e32 v30, 16, v46
	v_and_b32_e32 v31, 0xffff0000, v46
	v_lshlrev_b32_e32 v32, 16, v47
	v_and_b32_e32 v33, 0xffff0000, v47
	v_pk_add_f32 v[24:25], v[24:25], v[28:29]
	v_pk_add_f32 v[22:23], v[22:23], v[26:27]
	v_pk_add_f32 v[20:21], v[20:21], v[32:33]
	s_and_b64 vcc, exec, s[46:47]
	v_pk_add_f32 v[18:19], v[18:19], v[30:31]
	s_cbranch_vccnz .LBB0_1757
	global_store_dwordx4 v[54:55], v[22:25], off offset:512
	global_store_dwordx4 v[54:55], v[18:21], off offset:528

;     __device__ __forceinline__ void operator()(const f32x4 (&acc)[2][2][4][2], const Unit& u, int wr, int wc, int fr, int fq) const {
;     ...
;             for (int m = m0; m < m0 + 2; ++m) { const int row = row0 + ai * HALF + m * 16;
;                 float ss = 0.f;
; #pragma unroll
;                 for (int bj = 0; bj < 2; ++bj) { const f32x4 v0 = acc[ai][bj][m][0] + rv[m][bj][0], v1 = acc[ai][bj][m][1] + rv[m][bj][1];
;                     if (out) { float* op = out + (size_t)row * D + col0 + bj * HALF; *(f32x4*)op = v0; *(f32x4*)(op + 4) = v1; }
.LBB0_1761:
	v_lshlrev_b32_e32 v18, 16, v40
	v_and_b32_e32 v19, 0xffff0000, v40
	v_lshlrev_b64 v[26:27], 13, v[50:51]
	v_lshlrev_b32_e32 v20, 16, v41
	v_and_b32_e32 v21, 0xffff0000, v41
	v_lshlrev_b32_e32 v22, 16, v42
	s_waitcnt lgkmcnt(0)
	v_and_b32_e32 v23, 0xffff0000, v42
	v_lshlrev_b32_e32 v24, 16, v43
	v_and_b32_e32 v25, 0xffff0000, v43
	v_pk_add_f32 v[14:15], v[14:15], v[18:19]
	v_lshl_add_u64 v[18:19], s[12:13], 0, v[26:27]
	v_pk_add_f32 v[16:17], v[16:17], v[20:21]
	v_pk_add_f32 v[12:13], v[12:13], v[24:25]
	v_pk_add_f32 v[10:11], v[10:11], v[22:23]
	s_and_b64 vcc, exec, s[46:47]
	v_lshl_add_u64 v[20:21], v[156:157], 2, v[18:19]
	s_cbranch_vccnz .LBB0_1763
	global_store_dwordx4 v[20:21], v[14:17], off
	global_store_dwordx4 v[20:21], v[10:13], off offset:16

;     __device__ __forceinline__ void operator()(const f32x4 (&acc)[2][2][4][2], const Unit& u, int wr, int wc, int fr, int fq) const {
;     ...
;             for (int m = m0; m < m0 + 2; ++m) { const int row = row0 + ai * HALF + m * 16;
;                 float ss = 0.f;
; #pragma unroll
;                 for (int bj = 0; bj < 2; ++bj) { const f32x4 v0 = acc[ai][bj][m][0] + rv[m][bj][0], v1 = acc[ai][bj][m][1] + rv[m][bj][1];
;                     if (out) { float* op = out + (size_t)row * D + col0 + bj * HALF; *(f32x4*)op = v0; *(f32x4*)(op + 4) = v1; }
.LBB0_1766:
	v_lshlrev_b32_e32 v10, 16, v36
	v_and_b32_e32 v11, 0xffff0000, v36
	v_lshlrev_b32_e32 v12, 16, v37
	v_and_b32_e32 v13, 0xffff0000, v37
	v_lshlrev_b32_e32 v14, 16, v38
	v_and_b32_e32 v15, 0xffff0000, v38
	v_lshlrev_b32_e32 v16, 16, v39
	v_and_b32_e32 v17, 0xffff0000, v39
	v_pk_add_f32 v[8:9], v[8:9], v[12:13]
	v_pk_add_f32 v[6:7], v[6:7], v[10:11]
	v_pk_add_f32 v[4:5], v[4:5], v[16:17]
	s_and_b64 vcc, exec, s[46:47]
	v_pk_add_f32 v[2:3], v[2:3], v[14:15]
	s_cbranch_vccnz .LBB0_1768
	global_store_dwordx4 v[20:21], v[6:9], off offset:512
	global_store_dwordx4 v[20:21], v[2:5], off offset:528
